# P13 sample rows hand-written: 8 partial slabs + x1 + gate row streamed through one software pipeline (no separately waited batches), DPP wave sum
# speedup vs baseline: 1.0038x; 1.0038x over previous
; __device__ __forceinline__ void load_mo_row(f32x4 (&v)[8], const bf16_t* Ob, const float* Os, int row, int lane) {
;     ...
;     else { const f32x4* mr = (const f32x4*)(Os + (size_t)(row - MPROMPT) * DM) + lane;
; #pragma unroll
;         for (int j = 0; j < 8; ++j) v[j] = __builtin_nontemporal_load(mr + 64 * j);
; #pragma unroll 1
;         for (int k0 = 1; k0 < 8; k0 += 4) { f32x4 t[4][8];
; #pragma unroll
;             for (int q = 0; q < 4; ++q)
; #pragma unroll
;                 for (int j = 0; j < 8; ++j) t[q][j] = (k0 + q < 8) ? mr[(size_t)(k0 + q) * (1024 * DM / 4) + 64 * j] : (f32x4){0.f, 0.f, 0.f, 0.f};
; #pragma unroll
;             for (int q = 0; q < 4; ++q)
; #pragma unroll
;                 for (int j = 0; j < 8; ++j) v[j] += t[q][j]; } }
; __device__ __forceinline__ void phase_final(const Params& p) {
;     ...
;     for (int row = MPROMPT + (gw >> 1); (gw & 1) == 0 && row < MTOK; row += (NGW >> 1)) {
;         f32x4 v[8]; float ss = 0.f;
;         load_mo_row(v, Ob, Os, row, lane);
; #pragma unroll
;         for (int j = 0; j < 8; ++j) ss += (v[j].x * v[j].x + v[j].y * v[j].y) + (v[j].z * v[j].z + v[j].w * v[j].w);
;         const float rstd = 1.0f / sqrtf(wave_sum(ss) * (1.0f / DM) + EPS);
;         const float* ar = ada + (size_t)seq_of_row(row) * NADA;
; #pragma unroll
;         for (int j = 0; j < 8; ++j) { const int col = 4 * lane + 256 * j;
;             const f32x4 gt2 = *(const f32x4*)(ar + 5 * DM + col);
;             float* o = p.out + (size_t)row * DM + col; const f32x4 x1 = *(const f32x4*)o;
.LBB0_1447:
	s_or_b64 exec, exec, s[4:5]
	v_readlane_b32 s2, v255, 10
	v_readlane_b32 s3, v255, 11
	s_and_saveexec_b64 s[0:1], s[2:3]
	s_cbranch_execz .LBB0_1472
	v_and_b32_e32 v0, 63, v212
	v_readfirstlane_b32 s4, v216
	v_readlane_b32 s8, v254, 47
	v_readlane_b32 s9, v254, 48
	v_lshlrev_b32_e32 v1, 4, v0
	v_add_u32_e32 v2, 0x1000, v1
	s_lshl_b32 s5, s4, 13
	s_add_u32 s6, s84, 0x14900000
	s_addc_u32 s7, s85, 0
	s_add_u32 s6, s6, s5
	s_addc_u32 s7, s7, 0
	s_add_i32 s10, s4, 0x2000
	s_lshl_b32 s10, s10, 13
	s_add_u32 s8, s8, s10
	s_addc_u32 s9, s9, 0
	s_lshr_b32 s11, s4, 3
	s_add_i32 s11, s11, 4
	s_mul_i32 s11, s11, 0xc000
	s_add_i32 s11, s11, 0xa000
	s_add_u32 s12, s84, s11
	s_addc_u32 s13, s85, 0
	global_load_dwordx4 v[8:11], v1, s[6:7]
	global_load_dwordx4 v[12:15], v1, s[6:7] offset:1024
	global_load_dwordx4 v[16:19], v1, s[6:7] offset:2048
	global_load_dwordx4 v[20:23], v1, s[6:7] offset:3072
	global_load_dwordx4 v[24:27], v2, s[6:7]
	global_load_dwordx4 v[28:31], v2, s[6:7] offset:1024
	global_load_dwordx4 v[32:35], v2, s[6:7] offset:2048
	global_load_dwordx4 v[36:39], v2, s[6:7] offset:3072
	s_add_u32 s6, s6, 0x800000
	s_addc_u32 s7, s7, 0
	global_load_dwordx4 v[40:43], v1, s[6:7]
	global_load_dwordx4 v[44:47], v1, s[6:7] offset:1024
	global_load_dwordx4 v[48:51], v1, s[6:7] offset:2048
	global_load_dwordx4 v[52:55], v1, s[6:7] offset:3072
	global_load_dwordx4 v[56:59], v2, s[6:7]
	global_load_dwordx4 v[60:63], v2, s[6:7] offset:1024
	global_load_dwordx4 v[64:67], v2, s[6:7] offset:2048
	global_load_dwordx4 v[68:71], v2, s[6:7] offset:3072
	s_add_u32 s6, s6, 0x800000
	s_addc_u32 s7, s7, 0
	global_load_dwordx4 v[72:75], v1, s[6:7]
	global_load_dwordx4 v[76:79], v1, s[6:7] offset:1024
	global_load_dwordx4 v[80:83], v1, s[6:7] offset:2048
	global_load_dwordx4 v[84:87], v1, s[6:7] offset:3072
	global_load_dwordx4 v[88:91], v2, s[6:7]
	global_load_dwordx4 v[92:95], v2, s[6:7] offset:1024
	global_load_dwordx4 v[96:99], v2, s[6:7] offset:2048
	global_load_dwordx4 v[100:103], v2, s[6:7] offset:3072
	s_add_u32 s6, s6, 0x800000
	s_addc_u32 s7, s7, 0
	global_load_dwordx4 v[104:107], v1, s[6:7]
	global_load_dwordx4 v[108:111], v1, s[6:7] offset:1024
	global_load_dwordx4 v[112:115], v1, s[6:7] offset:2048
	global_load_dwordx4 v[116:119], v1, s[6:7] offset:3072
	global_load_dwordx4 v[120:123], v2, s[6:7]
	global_load_dwordx4 v[124:127], v2, s[6:7] offset:1024
	global_load_dwordx4 v[128:131], v2, s[6:7] offset:2048
	global_load_dwordx4 v[132:135], v2, s[6:7] offset:3072
	s_add_u32 s6, s6, 0x800000
	s_addc_u32 s7, s7, 0
	global_load_dwordx4 v[136:139], v1, s[8:9]
	global_load_dwordx4 v[140:143], v1, s[8:9] offset:1024
	global_load_dwordx4 v[144:147], v1, s[8:9] offset:2048
	global_load_dwordx4 v[148:151], v1, s[8:9] offset:3072
	global_load_dwordx4 v[152:155], v2, s[8:9]
	global_load_dwordx4 v[156:159], v2, s[8:9] offset:1024
	global_load_dwordx4 v[160:163], v2, s[8:9] offset:2048
	global_load_dwordx4 v[164:167], v2, s[8:9] offset:3072
	global_load_dwordx4 v[168:171], v1, s[12:13]
	global_load_dwordx4 v[172:175], v1, s[12:13] offset:1024
	global_load_dwordx4 v[176:179], v1, s[12:13] offset:2048
	global_load_dwordx4 v[180:183], v1, s[12:13] offset:3072
	global_load_dwordx4 v[184:187], v2, s[12:13]
	global_load_dwordx4 v[188:191], v2, s[12:13] offset:1024
	global_load_dwordx4 v[192:195], v2, s[12:13] offset:2048
	global_load_dwordx4 v[196:199], v2, s[12:13] offset:3072
	s_waitcnt vmcnt(32)
	v_pk_add_f32 v[8:9], v[8:9], v[40:41]
	v_pk_add_f32 v[10:11], v[10:11], v[42:43]
	v_pk_add_f32 v[12:13], v[12:13], v[44:45]
	v_pk_add_f32 v[14:15], v[14:15], v[46:47]
	v_pk_add_f32 v[16:17], v[16:17], v[48:49]
	v_pk_add_f32 v[18:19], v[18:19], v[50:51]
	v_pk_add_f32 v[20:21], v[20:21], v[52:53]
	v_pk_add_f32 v[22:23], v[22:23], v[54:55]
	v_pk_add_f32 v[24:25], v[24:25], v[56:57]
	v_pk_add_f32 v[26:27], v[26:27], v[58:59]
	v_pk_add_f32 v[28:29], v[28:29], v[60:61]
	v_pk_add_f32 v[30:31], v[30:31], v[62:63]
	v_pk_add_f32 v[32:33], v[32:33], v[64:65]
	v_pk_add_f32 v[34:35], v[34:35], v[66:67]
	v_pk_add_f32 v[36:37], v[36:37], v[68:69]
	v_pk_add_f32 v[38:39], v[38:39], v[70:71]
	global_load_dwordx4 v[40:43], v1, s[6:7]
	global_load_dwordx4 v[44:47], v1, s[6:7] offset:1024
	global_load_dwordx4 v[48:51], v1, s[6:7] offset:2048
	global_load_dwordx4 v[52:55], v1, s[6:7] offset:3072
	global_load_dwordx4 v[56:59], v2, s[6:7]
	global_load_dwordx4 v[60:63], v2, s[6:7] offset:1024
	global_load_dwordx4 v[64:67], v2, s[6:7] offset:2048
	global_load_dwordx4 v[68:71], v2, s[6:7] offset:3072
	s_add_u32 s6, s6, 0x800000
	s_addc_u32 s7, s7, 0
	s_waitcnt vmcnt(32)
	v_pk_add_f32 v[8:9], v[8:9], v[72:73]
	v_pk_add_f32 v[10:11], v[10:11], v[74:75]
	v_pk_add_f32 v[12:13], v[12:13], v[76:77]
	v_pk_add_f32 v[14:15], v[14:15], v[78:79]
	v_pk_add_f32 v[16:17], v[16:17], v[80:81]
	v_pk_add_f32 v[18:19], v[18:19], v[82:83]
	v_pk_add_f32 v[20:21], v[20:21], v[84:85]
	v_pk_add_f32 v[22:23], v[22:23], v[86:87]
	v_pk_add_f32 v[24:25], v[24:25], v[88:89]
	v_pk_add_f32 v[26:27], v[26:27], v[90:91]
	v_pk_add_f32 v[28:29], v[28:29], v[92:93]
	v_pk_add_f32 v[30:31], v[30:31], v[94:95]
	v_pk_add_f32 v[32:33], v[32:33], v[96:97]
	v_pk_add_f32 v[34:35], v[34:35], v[98:99]
	v_pk_add_f32 v[36:37], v[36:37], v[100:101]
	v_pk_add_f32 v[38:39], v[38:39], v[102:103]
	global_load_dwordx4 v[72:75], v1, s[6:7]
	global_load_dwordx4 v[76:79], v1, s[6:7] offset:1024
	global_load_dwordx4 v[80:83], v1, s[6:7] offset:2048
	global_load_dwordx4 v[84:87], v1, s[6:7] offset:3072
	global_load_dwordx4 v[88:91], v2, s[6:7]
	global_load_dwordx4 v[92:95], v2, s[6:7] offset:1024
	global_load_dwordx4 v[96:99], v2, s[6:7] offset:2048
	global_load_dwordx4 v[100:103], v2, s[6:7] offset:3072
	s_add_u32 s6, s6, 0x800000
	s_addc_u32 s7, s7, 0
	s_waitcnt vmcnt(32)
; __device__ __forceinline__ void load_mo_row(f32x4 (&v)[8], const bf16_t* Ob, const float* Os, int row, int lane) {
;     ...
;     else { const f32x4* mr = (const f32x4*)(Os + (size_t)(row - MPROMPT) * DM) + lane;
; #pragma unroll
;         for (int j = 0; j < 8; ++j) v[j] = __builtin_nontemporal_load(mr + 64 * j);
; #pragma unroll 1
;         for (int k0 = 1; k0 < 8; k0 += 4) { f32x4 t[4][8];
; #pragma unroll
;             for (int q = 0; q < 4; ++q)
; #pragma unroll
;                 for (int j = 0; j < 8; ++j) t[q][j] = (k0 + q < 8) ? mr[(size_t)(k0 + q) * (1024 * DM / 4) + 64 * j] : (f32x4){0.f, 0.f, 0.f, 0.f};
; #pragma unroll
;             for (int q = 0; q < 4; ++q)
; #pragma unroll
;                 for (int j = 0; j < 8; ++j) v[j] += t[q][j]; } }
	v_pk_add_f32 v[8:9], v[8:9], v[104:105]
	v_pk_add_f32 v[10:11], v[10:11], v[106:107]
	v_pk_add_f32 v[12:13], v[12:13], v[108:109]
	v_pk_add_f32 v[14:15], v[14:15], v[110:111]
	v_pk_add_f32 v[16:17], v[16:17], v[112:113]
	v_pk_add_f32 v[18:19], v[18:19], v[114:115]
	v_pk_add_f32 v[20:21], v[20:21], v[116:117]
	v_pk_add_f32 v[22:23], v[22:23], v[118:119]
	v_pk_add_f32 v[24:25], v[24:25], v[120:121]
	v_pk_add_f32 v[26:27], v[26:27], v[122:123]
	v_pk_add_f32 v[28:29], v[28:29], v[124:125]
	v_pk_add_f32 v[30:31], v[30:31], v[126:127]
	v_pk_add_f32 v[32:33], v[32:33], v[128:129]
	v_pk_add_f32 v[34:35], v[34:35], v[130:131]
	v_pk_add_f32 v[36:37], v[36:37], v[132:133]
	v_pk_add_f32 v[38:39], v[38:39], v[134:135]
	global_load_dwordx4 v[104:107], v1, s[6:7]
	global_load_dwordx4 v[108:111], v1, s[6:7] offset:1024
	global_load_dwordx4 v[112:115], v1, s[6:7] offset:2048
	global_load_dwordx4 v[116:119], v1, s[6:7] offset:3072
	global_load_dwordx4 v[120:123], v2, s[6:7]
	global_load_dwordx4 v[124:127], v2, s[6:7] offset:1024
	global_load_dwordx4 v[128:131], v2, s[6:7] offset:2048
	global_load_dwordx4 v[132:135], v2, s[6:7] offset:3072
	s_add_u32 s6, s6, 0x800000
	s_addc_u32 s7, s7, 0
	s_waitcnt vmcnt(16)
	v_pk_add_f32 v[8:9], v[8:9], v[40:41]
	v_pk_add_f32 v[10:11], v[10:11], v[42:43]
	v_pk_add_f32 v[12:13], v[12:13], v[44:45]
	v_pk_add_f32 v[14:15], v[14:15], v[46:47]
	v_pk_add_f32 v[16:17], v[16:17], v[48:49]
	v_pk_add_f32 v[18:19], v[18:19], v[50:51]
	v_pk_add_f32 v[20:21], v[20:21], v[52:53]
	v_pk_add_f32 v[22:23], v[22:23], v[54:55]
	v_pk_add_f32 v[24:25], v[24:25], v[56:57]
	v_pk_add_f32 v[26:27], v[26:27], v[58:59]
	v_pk_add_f32 v[28:29], v[28:29], v[60:61]
	v_pk_add_f32 v[30:31], v[30:31], v[62:63]
	v_pk_add_f32 v[32:33], v[32:33], v[64:65]
	v_pk_add_f32 v[34:35], v[34:35], v[66:67]
	v_pk_add_f32 v[36:37], v[36:37], v[68:69]
	v_pk_add_f32 v[38:39], v[38:39], v[70:71]
	global_load_dwordx4 v[40:43], v1, s[6:7]
	global_load_dwordx4 v[44:47], v1, s[6:7] offset:1024
	global_load_dwordx4 v[48:51], v1, s[6:7] offset:2048
	global_load_dwordx4 v[52:55], v1, s[6:7] offset:3072
	global_load_dwordx4 v[56:59], v2, s[6:7]
	global_load_dwordx4 v[60:63], v2, s[6:7] offset:1024
	global_load_dwordx4 v[64:67], v2, s[6:7] offset:2048
	global_load_dwordx4 v[68:71], v2, s[6:7] offset:3072
	s_waitcnt vmcnt(16)
	v_pk_add_f32 v[8:9], v[8:9], v[72:73]
	v_pk_add_f32 v[10:11], v[10:11], v[74:75]
	v_pk_add_f32 v[12:13], v[12:13], v[76:77]
	v_pk_add_f32 v[14:15], v[14:15], v[78:79]
	v_pk_add_f32 v[16:17], v[16:17], v[80:81]
	v_pk_add_f32 v[18:19], v[18:19], v[82:83]
	v_pk_add_f32 v[20:21], v[20:21], v[84:85]
	v_pk_add_f32 v[22:23], v[22:23], v[86:87]
	v_pk_add_f32 v[24:25], v[24:25], v[88:89]
	v_pk_add_f32 v[26:27], v[26:27], v[90:91]
	v_pk_add_f32 v[28:29], v[28:29], v[92:93]
	v_pk_add_f32 v[30:31], v[30:31], v[94:95]
	v_pk_add_f32 v[32:33], v[32:33], v[96:97]
	v_pk_add_f32 v[34:35], v[34:35], v[98:99]
	v_pk_add_f32 v[36:37], v[36:37], v[100:101]
	v_pk_add_f32 v[38:39], v[38:39], v[102:103]
	s_waitcnt vmcnt(8)
	v_pk_add_f32 v[8:9], v[8:9], v[104:105]
	v_pk_add_f32 v[10:11], v[10:11], v[106:107]
	v_pk_add_f32 v[12:13], v[12:13], v[108:109]
	v_pk_add_f32 v[14:15], v[14:15], v[110:111]
	v_pk_add_f32 v[16:17], v[16:17], v[112:113]
	v_pk_add_f32 v[18:19], v[18:19], v[114:115]
	v_pk_add_f32 v[20:21], v[20:21], v[116:117]
	v_pk_add_f32 v[22:23], v[22:23], v[118:119]
	v_pk_add_f32 v[24:25], v[24:25], v[120:121]
	v_pk_add_f32 v[26:27], v[26:27], v[122:123]
	v_pk_add_f32 v[28:29], v[28:29], v[124:125]
	v_pk_add_f32 v[30:31], v[30:31], v[126:127]
	v_pk_add_f32 v[32:33], v[32:33], v[128:129]
	v_pk_add_f32 v[34:35], v[34:35], v[130:131]
	v_pk_add_f32 v[36:37], v[36:37], v[132:133]
	v_pk_add_f32 v[38:39], v[38:39], v[134:135]
	s_waitcnt vmcnt(0)
; __device__ __forceinline__ float wave_sum(float v) {
; #pragma unroll
;     for (int o = 1; o < 64; o <<= 1) v += __shfl_xor(v, o);
;     return v;
; __device__ __forceinline__ void phase_final(const Params& p) {
;     ...
;         f32x4 v[8]; float ss = 0.f;
;         load_mo_row(v, Ob, Os, row, lane);
; #pragma unroll
;         for (int j = 0; j < 8; ++j) ss += (v[j].x * v[j].x + v[j].y * v[j].y) + (v[j].z * v[j].z + v[j].w * v[j].w);
;         const float rstd = 1.0f / sqrtf(wave_sum(ss) * (1.0f / DM) + EPS);
;         const float* ar = ada + (size_t)seq_of_row(row) * NADA;
; #pragma unroll
;         for (int j = 0; j < 8; ++j) { const int col = 4 * lane + 256 * j;
;             const f32x4 gt2 = *(const f32x4*)(ar + 5 * DM + col);
;             float* o = p.out + (size_t)row * DM + col; const f32x4 x1 = *(const f32x4*)o;
;             *(f32x4*)o = x1 + gt2 * (v[j] * rstd); }
	v_pk_add_f32 v[8:9], v[8:9], v[40:41]
	v_pk_add_f32 v[10:11], v[10:11], v[42:43]
	v_pk_add_f32 v[12:13], v[12:13], v[44:45]
	v_pk_add_f32 v[14:15], v[14:15], v[46:47]
	v_pk_add_f32 v[16:17], v[16:17], v[48:49]
	v_pk_add_f32 v[18:19], v[18:19], v[50:51]
	v_pk_add_f32 v[20:21], v[20:21], v[52:53]
	v_pk_add_f32 v[22:23], v[22:23], v[54:55]
	v_pk_add_f32 v[24:25], v[24:25], v[56:57]
	v_pk_add_f32 v[26:27], v[26:27], v[58:59]
	v_pk_add_f32 v[28:29], v[28:29], v[60:61]
	v_pk_add_f32 v[30:31], v[30:31], v[62:63]
	v_pk_add_f32 v[32:33], v[32:33], v[64:65]
	v_pk_add_f32 v[34:35], v[34:35], v[66:67]
	v_pk_add_f32 v[36:37], v[36:37], v[68:69]
	v_pk_add_f32 v[38:39], v[38:39], v[70:71]
	v_mul_f32_e32 v200, v8, v8
	v_mul_f32_e32 v201, v9, v9
	v_mul_f32_e32 v202, v10, v10
	v_mul_f32_e32 v203, v11, v11
	v_fmac_f32_e32 v200, v12, v12
	v_fmac_f32_e32 v201, v13, v13
	v_fmac_f32_e32 v202, v14, v14
	v_fmac_f32_e32 v203, v15, v15
	v_fmac_f32_e32 v200, v16, v16
	v_fmac_f32_e32 v201, v17, v17
	v_fmac_f32_e32 v202, v18, v18
	v_fmac_f32_e32 v203, v19, v19
	v_fmac_f32_e32 v200, v20, v20
	v_fmac_f32_e32 v201, v21, v21
	v_fmac_f32_e32 v202, v22, v22
	v_fmac_f32_e32 v203, v23, v23
	v_fmac_f32_e32 v200, v24, v24
	v_fmac_f32_e32 v201, v25, v25
	v_fmac_f32_e32 v202, v26, v26
	v_fmac_f32_e32 v203, v27, v27
	v_fmac_f32_e32 v200, v28, v28
	v_fmac_f32_e32 v201, v29, v29
	v_fmac_f32_e32 v202, v30, v30
	v_fmac_f32_e32 v203, v31, v31
	v_fmac_f32_e32 v200, v32, v32
	v_fmac_f32_e32 v201, v33, v33
	v_fmac_f32_e32 v202, v34, v34
	v_fmac_f32_e32 v203, v35, v35
	v_fmac_f32_e32 v200, v36, v36
	v_fmac_f32_e32 v201, v37, v37
	v_fmac_f32_e32 v202, v38, v38
	v_fmac_f32_e32 v203, v39, v39
	v_add_f32_e32 v200, v200, v201
	v_add_f32_e32 v202, v202, v203
	v_add_f32_e32 v200, v200, v202
	s_nop 1
	v_add_f32_dpp v200, v200, v200 quad_perm:[1,0,3,2] row_mask:0xf bank_mask:0xf
	s_nop 1
	v_add_f32_dpp v200, v200, v200 quad_perm:[2,3,0,1] row_mask:0xf bank_mask:0xf
	s_nop 1
	v_add_f32_dpp v200, v200, v200 row_half_mirror row_mask:0xf bank_mask:0xf
	s_nop 1
	v_add_f32_dpp v200, v200, v200 row_mirror row_mask:0xf bank_mask:0xf
	s_nop 1
	v_add_f32_dpp v200, v200, v200 row_bcast:15 row_mask:0xa bank_mask:0xf
	s_nop 1
	v_add_f32_dpp v200, v200, v200 row_bcast:31 row_mask:0xc bank_mask:0xf
	s_nop 1
	v_readlane_b32 s20, v200, 63
	v_mov_b32_e32 v224, 0x358637bd
	v_mov_b32_e32 v225, 0x260
	s_mov_b32 s17, 0xf800000
	v_mov_b32_e32 v204, s20
	v_fmamk_f32 v204, v204, 0x3a000000, v224
	v_mul_f32_e32 v205, 0x4f800000, v204
	v_cmp_gt_f32_e32 vcc, s17, v204
	s_nop 1
	v_cndmask_b32_e32 v204, v204, v205, vcc
	v_sqrt_f32_e32 v205, v204
	s_nop 0
	v_add_u32_e32 v206, -1, v205
	v_fma_f32 v207, -v206, v205, v204
	v_cmp_ge_f32_e64 s[0:1], 0, v207
	v_add_u32_e32 v207, 1, v205
	s_nop 0
	v_cndmask_b32_e64 v206, v205, v206, s[0:1]
	v_fma_f32 v205, -v207, v205, v204
	v_cmp_lt_f32_e64 s[0:1], 0, v205
	s_nop 1
	v_cndmask_b32_e64 v205, v206, v207, s[0:1]
	v_mul_f32_e32 v206, 0x37800000, v205
	v_cndmask_b32_e32 v205, v205, v206, vcc
	v_cmp_class_f32_e32 vcc, v204, v225
	s_nop 1
	v_cndmask_b32_e32 v204, v205, v204, vcc
	v_div_scale_f32 v205, s[0:1], v204, v204, 1.0
	v_rcp_f32_e32 v206, v205
	s_nop 0
	v_fma_f32 v207, -v205, v206, 1.0
	v_fmac_f32_e32 v206, v207, v206
	v_div_scale_f32 v207, vcc, 1.0, v204, 1.0
	v_mul_f32_e32 v208, v207, v206
	v_fma_f32 v209, -v205, v208, v207
	v_fmac_f32_e32 v208, v209, v206
	v_fma_f32 v205, -v205, v208, v207
	v_div_fmas_f32 v205, v205, v206, v208
	v_div_fixup_f32 v204, v205, v204, 1.0
	v_pk_mul_f32 v[8:9], v[8:9], v[204:205] op_sel_hi:[1,0]
	v_pk_mul_f32 v[10:11], v[10:11], v[204:205] op_sel_hi:[1,0]
	v_pk_mul_f32 v[12:13], v[12:13], v[204:205] op_sel_hi:[1,0]
	v_pk_mul_f32 v[14:15], v[14:15], v[204:205] op_sel_hi:[1,0]
	v_pk_mul_f32 v[16:17], v[16:17], v[204:205] op_sel_hi:[1,0]
	v_pk_mul_f32 v[18:19], v[18:19], v[204:205] op_sel_hi:[1,0]
	v_pk_mul_f32 v[20:21], v[20:21], v[204:205] op_sel_hi:[1,0]
	v_pk_mul_f32 v[22:23], v[22:23], v[204:205] op_sel_hi:[1,0]
	v_pk_mul_f32 v[24:25], v[24:25], v[204:205] op_sel_hi:[1,0]
	v_pk_mul_f32 v[26:27], v[26:27], v[204:205] op_sel_hi:[1,0]
	v_pk_mul_f32 v[28:29], v[28:29], v[204:205] op_sel_hi:[1,0]
	v_pk_mul_f32 v[30:31], v[30:31], v[204:205] op_sel_hi:[1,0]
	v_pk_mul_f32 v[32:33], v[32:33], v[204:205] op_sel_hi:[1,0]
	v_pk_mul_f32 v[34:35], v[34:35], v[204:205] op_sel_hi:[1,0]
	v_pk_mul_f32 v[36:37], v[36:37], v[204:205] op_sel_hi:[1,0]
	v_pk_mul_f32 v[38:39], v[38:39], v[204:205] op_sel_hi:[1,0]
	v_pk_fma_f32 v[8:9], v[168:169], v[8:9], v[136:137]
	v_pk_fma_f32 v[10:11], v[170:171], v[10:11], v[138:139]
	v_pk_fma_f32 v[12:13], v[172:173], v[12:13], v[140:141]
	v_pk_fma_f32 v[14:15], v[174:175], v[14:15], v[142:143]
	v_pk_fma_f32 v[16:17], v[176:177], v[16:17], v[144:145]
	v_pk_fma_f32 v[18:19], v[178:179], v[18:19], v[146:147]
	v_pk_fma_f32 v[20:21], v[180:181], v[20:21], v[148:149]
	v_pk_fma_f32 v[22:23], v[182:183], v[22:23], v[150:151]
	v_pk_fma_f32 v[24:25], v[184:185], v[24:25], v[152:153]
	v_pk_fma_f32 v[26:27], v[186:187], v[26:27], v[154:155]
	v_pk_fma_f32 v[28:29], v[188:189], v[28:29], v[156:157]
	v_pk_fma_f32 v[30:31], v[190:191], v[30:31], v[158:159]
	v_pk_fma_f32 v[32:33], v[192:193], v[32:33], v[160:161]
	v_pk_fma_f32 v[34:35], v[194:195], v[34:35], v[162:163]
	v_pk_fma_f32 v[36:37], v[196:197], v[36:37], v[164:165]
	v_pk_fma_f32 v[38:39], v[198:199], v[38:39], v[166:167]
	global_store_dwordx4 v1, v[8:11], s[8:9]
	global_store_dwordx4 v1, v[12:15], s[8:9] offset:1024
	global_store_dwordx4 v1, v[16:19], s[8:9] offset:2048
	global_store_dwordx4 v1, v[20:23], s[8:9] offset:3072
	global_store_dwordx4 v2, v[24:27], s[8:9]
	global_store_dwordx4 v2, v[28:31], s[8:9] offset:1024
	global_store_dwordx4 v2, v[32:35], s[8:9] offset:2048
	global_store_dwordx4 v2, v[36:39], s[8:9] offset:3072
